# diff-attn QK: counted lgkmcnt waits so the first QK MFMAs start when the first K fragments land
# speedup vs baseline: 1.0069x; 1.0035x over previous
; #define MFMA32(a, b, c) __builtin_amdgcn_mfma_f32_32x32x16_bf16((a), (b), (c), 0, 0, 0)
; DI void diff_unit(unsigned char* smem, const bf16* __restrict__ QKV, bf16* __restrict__ Y, int h, int qb, float lam, float outscale, const float* __restrict__ gain, float kn0, float kn1, int tid) {
;     ...
;                 __builtin_amdgcn_sched_barrier(0);
; #pragma unroll
;                 for (int ds = 0; ds < 4; ++ds)
; #pragma unroll
;                     for (int kh = 0; kh < 2; ++kh) p[kh] = MFMA32(kf[kh * 4 + ds], qf[ds], p[kh]);
;                 __builtin_amdgcn_sched_barrier(0);
.Lmy_ci_fast:
	v_add_u32_e32 v159, v191, v190
	v_add_u32_e32 v161, 0xffffffbf, v159
	s_waitcnt lgkmcnt(6)
	v_mfma_f32_32x32x16_bf16 v[80:95], v[140:143], v[112:115], v[220:235]
	v_mfma_f32_32x32x16_bf16 v[96:111], v[144:147], v[112:115], v[236:251]
.Lmy_ci_join:
	s_waitcnt lgkmcnt(4)
	v_mfma_f32_32x32x16_bf16 v[80:95], v[136:139], v[116:119], v[80:95]
	v_mfma_f32_32x32x16_bf16 v[96:111], v[132:135], v[116:119], v[96:111]
	s_waitcnt lgkmcnt(2)
	v_mfma_f32_32x32x16_bf16 v[80:95], v[128:131], v[120:123], v[80:95]
	v_mfma_f32_32x32x16_bf16 v[96:111], v[42:45], v[120:123], v[96:111]
	s_waitcnt lgkmcnt(0)
	v_mfma_f32_32x32x16_bf16 v[80:95], v[38:41], v[124:127], v[80:95]
	v_mfma_f32_32x32x16_bf16 v[96:111], v[34:37], v[124:127], v[96:111]
	s_cmp_eq_u32 s61, 0
	s_cbranch_scc1 .Lmy_dma_mid_skip
	s_cmp_eq_u64 s[14:15], 0
	s_cbranch_scc1 .Lmy_dma_mid_skip
	v_add_u32_e32 v214, -2, v192
	v_mul_lo_u32 v214, v214, s53
	v_mov_b32_e32 v215, 0
	s_sub_i32 s32, s63, s45
	v_lshl_add_u64 v[212:213], v[154:155], 0, v[214:215]
	v_lshl_add_u64 v[216:217], v[156:157], 0, v[214:215]
	v_lshl_add_u64 v[214:215], v[212:213], 0, s[86:87]
	s_add_i32 m0, s32, 0x10000
	s_nop 0
	global_load_lds_dwordx4 v[214:215], off
	s_add_i32 m0, s32, 0x14000
	v_lshl_add_u64 v[214:215], v[212:213], 0, s[88:89]
	global_load_lds_dwordx4 v[216:217], off
	s_add_i32 m0, s32, 0x11000
	s_nop 0
	global_load_lds_dwordx4 v[214:215], off
	v_lshl_add_u64 v[214:215], v[216:217], 0, s[90:91]
	s_add_i32 m0, s32, 0x15000
	s_nop 0
	global_load_lds_dwordx4 v[214:215], off
	v_lshl_add_u64 v[214:215], v[212:213], 0, s[92:93]
	s_add_i32 m0, s32, 0x12000
	v_lshl_add_u64 v[212:213], v[212:213], 0, s[96:97]
	global_load_lds_dwordx4 v[214:215], off
	v_lshl_add_u64 v[214:215], v[216:217], 0, s[94:95]
	s_add_i32 m0, s32, 0x16000
	s_nop 0
	global_load_lds_dwordx4 v[214:215], off
	s_add_i32 m0, s32, 0x13000
	s_nop 0
	global_load_lds_dwordx4 v[212:213], off
	v_lshl_add_u64 v[212:213], v[216:217], 0, s[72:73]
	s_add_i32 m0, s32, 0x17000
	s_nop 0
	global_load_lds_dwordx4 v[212:213], off
